# G2 and F3 residual epilogues rewritten: three rows of the residual input in flight, SGPR-base addressing, no initial full drain
# speedup vs baseline: 1.0025x; 1.0025x over previous
; #define NTL(p) __builtin_nontemporal_load((const f32x4*)(p))
; #define NTS(v, p) __builtin_nontemporal_store((v), (f32x4*)(p))
; __device__ __forceinline__ unsigned cvt_pk_bf16(float lo, float hi) { unsigned r; asm volatile("v_cvt_pk_bf16_f32 %0, %1, %2" : "=v"(r) : "v"(lo), "v"(hi)); return r; }
;     __device__ __forceinline__ void operator()(AccT& acc, const Unit& u, int wr, int wc, int fr, int fq) const {
;     ...
;         const int row0 = u.pm * 256 + wr * 64 + fr, col0 = u.pn * 256 + wc * 32 + 8 * fq;
;         f32x4 xv[2][4];
;         { const int row = row0; const float* xr = (row < HALF_TOK ? x0 + (size_t)row * DM : x1 + (size_t)(row - HALF_TOK) * DM) + col0;
;           xv[0][0] = NTL(xr); xv[0][1] = NTL(xr + 4); xv[0][2] = NTL(xr + 128); xv[0][3] = NTL(xr + 132); }
; #pragma unroll
;         for (int r = 0; r < 8; ++r) { const int ai = r >> 2, m = r & 3; const int row = row0 + ai * 128 + m * 16;
;             if (r < 7) { const int rn = row0 + ((r + 1) >> 2) * 128 + ((r + 1) & 3) * 16; const float* xr = (rn < HALF_TOK ? x0 + (size_t)rn * DM : x1 + (size_t)(rn - HALF_TOK) * DM) + col0;
;                 xv[(r + 1) & 1][0] = NTL(xr); xv[(r + 1) & 1][1] = NTL(xr + 4); xv[(r + 1) & 1][2] = NTL(xr + 128); xv[(r + 1) & 1][3] = NTL(xr + 132); }
;             float* hr = H + (size_t)row * DM + col0; float ss = 0.f;
; #pragma unroll
;             for (int bj = 0; bj < 2; ++bj) {
;                 f32x4 v0 = acc[ai][bj][m][0] + xv[r & 1][2 * bj], v1 = acc[ai][bj][m][1] + xv[r & 1][2 * bj + 1];
;                 NTS(v0, hr + bj * 128); NTS(v1, hr + bj * 128 + 4);
;                 u32x4 w; w.x = cvt_pk_bf16(v0[0], v0[1]); w.y = cvt_pk_bf16(v0[2], v0[3]); w.z = cvt_pk_bf16(v1[0], v1[1]); w.w = cvt_pk_bf16(v1[2], v1[3]);
;                 *(u32x4*)(HB + (size_t)row * DM + col0 + bj * 128) = w;
; #pragma unroll
;                 for (int j = 0; j < 4; ++j) ss += v0[j] * v0[j] + v1[j] * v1[j]; }
;             ss += __shfl_xor(ss, 16); ss += __shfl_xor(ss, 32);
;             if (fq == 0) unsafeAtomicAdd(rss + row, ss); __builtin_amdgcn_sched_barrier(0); }
.LBB0_48:
	s_lshl_b32 s16, s76, 8
	s_add_i32 s16, s16, s50
	v_add_u32_e32 v224, s16, v164
	s_lshl_b32 s16, s77, 8
	s_or_b32 s16, s16, s51
	v_readlane_b32 s60, v254, 34
	v_readlane_b32 s61, v254, 35
	v_readlane_b32 s62, v254, 36
	v_readlane_b32 s63, v254, 37
	s_nop 3
	s_sub_u32 s62, s62, 0x4000000
	s_subb_u32 s63, s63, 0
	s_cmp_lt_u32 s76, 64
	s_cselect_b32 s60, s60, s62
	s_cselect_b32 s61, s61, s63
	v_lshl_add_u32 v225, v165, 3, s16
	v_lshlrev_b32_e32 v158, 2, v224
	v_lshlrev_b32_e32 v225, 2, v225
	v_lshl_add_u32 v156, v224, 12, v225
	v_lshrrev_b32_e32 v157, 1, v156
	v_xor_b32_e32 v159, 16, v203
	v_xor_b32_e32 v160, 32, v203
	v_xor_b32_e32 v161, 48, v203
	v_lshlrev_b32_e32 v159, 2, v159
	v_lshlrev_b32_e32 v160, 2, v160
	v_lshlrev_b32_e32 v161, 2, v161
	v_cmp_eq_u32_e64 s[42:43], 0, v165
	global_load_dwordx4 v[130:133], v156, s[60:61] nt
	global_load_dwordx4 v[134:137], v156, s[60:61] offset:16 nt
	global_load_dwordx4 v[138:141], v156, s[60:61] offset:512 nt
	global_load_dwordx4 v[142:145], v156, s[60:61] offset:528 nt
	v_add_u32_e32 v227, 0x10000, v156
	global_load_dwordx4 v[170:173], v227, s[60:61] nt
	global_load_dwordx4 v[174:177], v227, s[60:61] offset:16 nt
	global_load_dwordx4 v[178:181], v227, s[60:61] offset:512 nt
	global_load_dwordx4 v[182:185], v227, s[60:61] offset:528 nt
	v_add_u32_e32 v227, 0x20000, v156
	global_load_dwordx4 v[188:191], v227, s[60:61] nt
	global_load_dwordx4 v[192:195], v227, s[60:61] offset:16 nt
	global_load_dwordx4 v[196:199], v227, s[60:61] offset:512 nt
	global_load_dwordx4 v[204:207], v227, s[60:61] offset:528 nt
	s_waitcnt vmcnt(8)
	v_pk_add_f32 v[122:123], v[122:123], v[130:131]
	v_pk_add_f32 v[124:125], v[124:125], v[132:133]
	v_pk_add_f32 v[126:127], v[126:127], v[134:135]
	v_pk_add_f32 v[128:129], v[128:129], v[136:137]
	v_pk_add_f32 v[118:119], v[118:119], v[138:139]
	v_pk_add_f32 v[120:121], v[120:121], v[140:141]
	v_pk_add_f32 v[114:115], v[114:115], v[142:143]
	v_pk_add_f32 v[116:117], v[116:117], v[144:145]
	global_store_dwordx4 v156, v[122:125], s[22:23] nt
	global_store_dwordx4 v156, v[126:129], s[22:23] offset:16 nt
	global_store_dwordx4 v156, v[118:121], s[22:23] offset:512 nt
	global_store_dwordx4 v156, v[114:117], s[22:23] offset:528 nt
	v_cvt_pk_bf16_f32 v130, v122, v123
	v_cvt_pk_bf16_f32 v131, v124, v125
	v_cvt_pk_bf16_f32 v132, v126, v127
	v_cvt_pk_bf16_f32 v133, v128, v129
	v_cvt_pk_bf16_f32 v134, v118, v119
	v_cvt_pk_bf16_f32 v135, v120, v121
	v_cvt_pk_bf16_f32 v136, v114, v115
	v_cvt_pk_bf16_f32 v137, v116, v117
	global_store_dwordx4 v157, v[130:133], s[6:7]
	global_store_dwordx4 v157, v[134:137], s[6:7] offset:256
	v_pk_mul_f32 v[222:223], v[122:123], v[122:123]
	s_nop 0
	v_pk_fma_f32 v[222:223], v[124:125], v[124:125], v[222:223]
	s_nop 0
	v_pk_fma_f32 v[222:223], v[126:127], v[126:127], v[222:223]
	s_nop 0
	v_pk_fma_f32 v[222:223], v[128:129], v[128:129], v[222:223]
	s_nop 0
	v_pk_fma_f32 v[222:223], v[118:119], v[118:119], v[222:223]
	s_nop 0
	v_pk_fma_f32 v[222:223], v[120:121], v[120:121], v[222:223]
	s_nop 0
	v_pk_fma_f32 v[222:223], v[114:115], v[114:115], v[222:223]
	s_nop 0
	v_pk_fma_f32 v[222:223], v[116:117], v[116:117], v[222:223]
	s_nop 1
	v_add_u32_e32 v227, 0x30000, v156
	global_load_dwordx4 v[130:133], v227, s[60:61] nt
	global_load_dwordx4 v[134:137], v227, s[60:61] offset:16 nt
	global_load_dwordx4 v[138:141], v227, s[60:61] offset:512 nt
	global_load_dwordx4 v[142:145], v227, s[60:61] offset:528 nt
	s_nop 0
	v_add_f32_e32 v222, v222, v223
	ds_bpermute_b32 v224, v159, v222
	ds_bpermute_b32 v225, v160, v222
	ds_bpermute_b32 v226, v161, v222
	s_waitcnt lgkmcnt(0)
	v_add_f32_e32 v222, v222, v224
	v_add_f32_e32 v225, v225, v226
	v_add_f32_e32 v222, v222, v225
	s_mov_b64 s[16:17], exec
	s_and_b64 exec, exec, s[42:43]
	global_atomic_add_f32 v158, v222, s[8:9]
	s_mov_b64 exec, s[16:17]
	s_waitcnt vmcnt(15)
	v_pk_add_f32 v[110:111], v[110:111], v[170:171]
	v_pk_add_f32 v[112:113], v[112:113], v[172:173]
	v_pk_add_f32 v[106:107], v[106:107], v[174:175]
	v_pk_add_f32 v[108:109], v[108:109], v[176:177]
	v_pk_add_f32 v[102:103], v[102:103], v[178:179]
	v_pk_add_f32 v[104:105], v[104:105], v[180:181]
	v_pk_add_f32 v[98:99], v[98:99], v[182:183]
	v_pk_add_f32 v[100:101], v[100:101], v[184:185]
	v_add_u32_e32 v228, 0x10000, v156
	v_add_u32_e32 v229, 0x8000, v157
	global_store_dwordx4 v228, v[110:113], s[22:23] nt
	global_store_dwordx4 v228, v[106:109], s[22:23] offset:16 nt
	global_store_dwordx4 v228, v[102:105], s[22:23] offset:512 nt
	global_store_dwordx4 v228, v[98:101], s[22:23] offset:528 nt
	v_cvt_pk_bf16_f32 v170, v110, v111
	v_cvt_pk_bf16_f32 v171, v112, v113
	v_cvt_pk_bf16_f32 v172, v106, v107
	v_cvt_pk_bf16_f32 v173, v108, v109
	v_cvt_pk_bf16_f32 v174, v102, v103
	v_cvt_pk_bf16_f32 v175, v104, v105
	v_cvt_pk_bf16_f32 v176, v98, v99
	v_cvt_pk_bf16_f32 v177, v100, v101
	global_store_dwordx4 v229, v[170:173], s[6:7]
	global_store_dwordx4 v229, v[174:177], s[6:7] offset:256
	v_pk_mul_f32 v[222:223], v[110:111], v[110:111]
	s_nop 0
	v_pk_fma_f32 v[222:223], v[112:113], v[112:113], v[222:223]
	s_nop 0
	v_pk_fma_f32 v[222:223], v[106:107], v[106:107], v[222:223]
	s_nop 0
	v_pk_fma_f32 v[222:223], v[108:109], v[108:109], v[222:223]
	s_nop 0
	v_pk_fma_f32 v[222:223], v[102:103], v[102:103], v[222:223]
	s_nop 0
	v_pk_fma_f32 v[222:223], v[104:105], v[104:105], v[222:223]
	s_nop 0
	v_pk_fma_f32 v[222:223], v[98:99], v[98:99], v[222:223]
	s_nop 0
	v_pk_fma_f32 v[222:223], v[100:101], v[100:101], v[222:223]
	s_nop 1
	v_add_u32_e32 v227, 0x80000, v156
	global_load_dwordx4 v[170:173], v227, s[60:61] nt
	global_load_dwordx4 v[174:177], v227, s[60:61] offset:16 nt
	global_load_dwordx4 v[178:181], v227, s[60:61] offset:512 nt
	global_load_dwordx4 v[182:185], v227, s[60:61] offset:528 nt
	s_nop 0
	v_add_f32_e32 v222, v222, v223
	ds_bpermute_b32 v224, v159, v222
	ds_bpermute_b32 v225, v160, v222
	ds_bpermute_b32 v226, v161, v222
	s_waitcnt lgkmcnt(0)
; #define NTL(p) __builtin_nontemporal_load((const f32x4*)(p))
; #define NTS(v, p) __builtin_nontemporal_store((v), (f32x4*)(p))
; __device__ __forceinline__ unsigned cvt_pk_bf16(float lo, float hi) { unsigned r; asm volatile("v_cvt_pk_bf16_f32 %0, %1, %2" : "=v"(r) : "v"(lo), "v"(hi)); return r; }
;     __device__ __forceinline__ void operator()(AccT& acc, const Unit& u, int wr, int wc, int fr, int fq) const {
;     ...
;         for (int r = 0; r < 8; ++r) { const int ai = r >> 2, m = r & 3; const int row = row0 + ai * 128 + m * 16;
;             if (r < 7) { const int rn = row0 + ((r + 1) >> 2) * 128 + ((r + 1) & 3) * 16; const float* xr = (rn < HALF_TOK ? x0 + (size_t)rn * DM : x1 + (size_t)(rn - HALF_TOK) * DM) + col0;
;                 xv[(r + 1) & 1][0] = NTL(xr); xv[(r + 1) & 1][1] = NTL(xr + 4); xv[(r + 1) & 1][2] = NTL(xr + 128); xv[(r + 1) & 1][3] = NTL(xr + 132); }
;             float* hr = H + (size_t)row * DM + col0; float ss = 0.f;
; #pragma unroll
;             for (int bj = 0; bj < 2; ++bj) {
;                 f32x4 v0 = acc[ai][bj][m][0] + xv[r & 1][2 * bj], v1 = acc[ai][bj][m][1] + xv[r & 1][2 * bj + 1];
;                 NTS(v0, hr + bj * 128); NTS(v1, hr + bj * 128 + 4);
;                 u32x4 w; w.x = cvt_pk_bf16(v0[0], v0[1]); w.y = cvt_pk_bf16(v0[2], v0[3]); w.z = cvt_pk_bf16(v1[0], v1[1]); w.w = cvt_pk_bf16(v1[2], v1[3]);
;                 *(u32x4*)(HB + (size_t)row * DM + col0 + bj * 128) = w;
; #pragma unroll
;                 for (int j = 0; j < 4; ++j) ss += v0[j] * v0[j] + v1[j] * v1[j]; }
;             ss += __shfl_xor(ss, 16); ss += __shfl_xor(ss, 32);
;             if (fq == 0) unsafeAtomicAdd(rss + row, ss); __builtin_amdgcn_sched_barrier(0); }
	v_add_f32_e32 v222, v222, v224
	v_add_f32_e32 v225, v225, v226
	v_add_f32_e32 v222, v222, v225
	s_mov_b64 s[16:17], exec
	s_and_b64 exec, exec, s[42:43]
	global_atomic_add_f32 v158, v222, s[8:9] offset:64
	s_mov_b64 exec, s[16:17]
	s_waitcnt vmcnt(22)
	v_pk_add_f32 v[94:95], v[94:95], v[188:189]
	v_pk_add_f32 v[96:97], v[96:97], v[190:191]
	v_pk_add_f32 v[90:91], v[90:91], v[192:193]
	v_pk_add_f32 v[92:93], v[92:93], v[194:195]
	v_pk_add_f32 v[86:87], v[86:87], v[196:197]
	v_pk_add_f32 v[88:89], v[88:89], v[198:199]
	v_pk_add_f32 v[82:83], v[82:83], v[204:205]
	v_pk_add_f32 v[84:85], v[84:85], v[206:207]
	v_add_u32_e32 v228, 0x20000, v156
	v_add_u32_e32 v229, 0x10000, v157
	global_store_dwordx4 v228, v[94:97], s[22:23] nt
	global_store_dwordx4 v228, v[90:93], s[22:23] offset:16 nt
	global_store_dwordx4 v228, v[86:89], s[22:23] offset:512 nt
	global_store_dwordx4 v228, v[82:85], s[22:23] offset:528 nt
	v_cvt_pk_bf16_f32 v188, v94, v95
	v_cvt_pk_bf16_f32 v189, v96, v97
	v_cvt_pk_bf16_f32 v190, v90, v91
	v_cvt_pk_bf16_f32 v191, v92, v93
	v_cvt_pk_bf16_f32 v192, v86, v87
	v_cvt_pk_bf16_f32 v193, v88, v89
	v_cvt_pk_bf16_f32 v194, v82, v83
	v_cvt_pk_bf16_f32 v195, v84, v85
	global_store_dwordx4 v229, v[188:191], s[6:7]
	global_store_dwordx4 v229, v[192:195], s[6:7] offset:256
	v_pk_mul_f32 v[222:223], v[94:95], v[94:95]
	s_nop 0
	v_pk_fma_f32 v[222:223], v[96:97], v[96:97], v[222:223]
	s_nop 0
	v_pk_fma_f32 v[222:223], v[90:91], v[90:91], v[222:223]
	s_nop 0
	v_pk_fma_f32 v[222:223], v[92:93], v[92:93], v[222:223]
	s_nop 0
	v_pk_fma_f32 v[222:223], v[86:87], v[86:87], v[222:223]
	s_nop 0
	v_pk_fma_f32 v[222:223], v[88:89], v[88:89], v[222:223]
	s_nop 0
	v_pk_fma_f32 v[222:223], v[82:83], v[82:83], v[222:223]
	s_nop 0
	v_pk_fma_f32 v[222:223], v[84:85], v[84:85], v[222:223]
	s_nop 1
	v_add_u32_e32 v227, 0x90000, v156
	global_load_dwordx4 v[188:191], v227, s[60:61] nt
	global_load_dwordx4 v[192:195], v227, s[60:61] offset:16 nt
	global_load_dwordx4 v[196:199], v227, s[60:61] offset:512 nt
	global_load_dwordx4 v[204:207], v227, s[60:61] offset:528 nt
	s_nop 0
	v_add_f32_e32 v222, v222, v223
	ds_bpermute_b32 v224, v159, v222
	ds_bpermute_b32 v225, v160, v222
	ds_bpermute_b32 v226, v161, v222
	s_waitcnt lgkmcnt(0)
	v_add_f32_e32 v222, v222, v224
	v_add_f32_e32 v225, v225, v226
	v_add_f32_e32 v222, v222, v225
	s_mov_b64 s[16:17], exec
	s_and_b64 exec, exec, s[42:43]
	global_atomic_add_f32 v158, v222, s[8:9] offset:128
	s_mov_b64 exec, s[16:17]
	s_waitcnt vmcnt(23)
	v_pk_add_f32 v[78:79], v[78:79], v[130:131]
	v_pk_add_f32 v[80:81], v[80:81], v[132:133]
	v_pk_add_f32 v[74:75], v[74:75], v[134:135]
	v_pk_add_f32 v[76:77], v[76:77], v[136:137]
	v_pk_add_f32 v[70:71], v[70:71], v[138:139]
	v_pk_add_f32 v[72:73], v[72:73], v[140:141]
	v_pk_add_f32 v[66:67], v[66:67], v[142:143]
	v_pk_add_f32 v[68:69], v[68:69], v[144:145]
	v_add_u32_e32 v228, 0x30000, v156
	v_add_u32_e32 v229, 0x18000, v157
	global_store_dwordx4 v228, v[78:81], s[22:23] nt
	global_store_dwordx4 v228, v[74:77], s[22:23] offset:16 nt
	global_store_dwordx4 v228, v[70:73], s[22:23] offset:512 nt
	global_store_dwordx4 v228, v[66:69], s[22:23] offset:528 nt
	v_cvt_pk_bf16_f32 v130, v78, v79
	v_cvt_pk_bf16_f32 v131, v80, v81
	v_cvt_pk_bf16_f32 v132, v74, v75
	v_cvt_pk_bf16_f32 v133, v76, v77
	v_cvt_pk_bf16_f32 v134, v70, v71
	v_cvt_pk_bf16_f32 v135, v72, v73
	v_cvt_pk_bf16_f32 v136, v66, v67
	v_cvt_pk_bf16_f32 v137, v68, v69
	global_store_dwordx4 v229, v[130:133], s[6:7]
	global_store_dwordx4 v229, v[134:137], s[6:7] offset:256
	v_pk_mul_f32 v[222:223], v[78:79], v[78:79]
	s_nop 0
	v_pk_fma_f32 v[222:223], v[80:81], v[80:81], v[222:223]
	s_nop 0
	v_pk_fma_f32 v[222:223], v[74:75], v[74:75], v[222:223]
	s_nop 0
	v_pk_fma_f32 v[222:223], v[76:77], v[76:77], v[222:223]
	s_nop 0
	v_pk_fma_f32 v[222:223], v[70:71], v[70:71], v[222:223]
	s_nop 0
	v_pk_fma_f32 v[222:223], v[72:73], v[72:73], v[222:223]
	s_nop 0
	v_pk_fma_f32 v[222:223], v[66:67], v[66:67], v[222:223]
	s_nop 0
	v_pk_fma_f32 v[222:223], v[68:69], v[68:69], v[222:223]
	s_nop 1
	v_add_u32_e32 v227, 0xa0000, v156
	global_load_dwordx4 v[130:133], v227, s[60:61] nt
	global_load_dwordx4 v[134:137], v227, s[60:61] offset:16 nt
	global_load_dwordx4 v[138:141], v227, s[60:61] offset:512 nt
	global_load_dwordx4 v[142:145], v227, s[60:61] offset:528 nt
	s_nop 0
	v_add_f32_e32 v222, v222, v223
	ds_bpermute_b32 v224, v159, v222
	ds_bpermute_b32 v225, v160, v222
	ds_bpermute_b32 v226, v161, v222
	s_waitcnt lgkmcnt(0)
	v_add_f32_e32 v222, v222, v224
	v_add_f32_e32 v225, v225, v226
	v_add_f32_e32 v222, v222, v225
	s_mov_b64 s[16:17], exec
	s_and_b64 exec, exec, s[42:43]
	global_atomic_add_f32 v158, v222, s[8:9] offset:192
	s_mov_b64 exec, s[16:17]
	s_waitcnt vmcnt(23)
; #define NTL(p) __builtin_nontemporal_load((const f32x4*)(p))
; #define NTS(v, p) __builtin_nontemporal_store((v), (f32x4*)(p))
; __device__ __forceinline__ unsigned cvt_pk_bf16(float lo, float hi) { unsigned r; asm volatile("v_cvt_pk_bf16_f32 %0, %1, %2" : "=v"(r) : "v"(lo), "v"(hi)); return r; }
;     __device__ __forceinline__ void operator()(AccT& acc, const Unit& u, int wr, int wc, int fr, int fq) const {
;     ...
;         for (int r = 0; r < 8; ++r) { const int ai = r >> 2, m = r & 3; const int row = row0 + ai * 128 + m * 16;
;             if (r < 7) { const int rn = row0 + ((r + 1) >> 2) * 128 + ((r + 1) & 3) * 16; const float* xr = (rn < HALF_TOK ? x0 + (size_t)rn * DM : x1 + (size_t)(rn - HALF_TOK) * DM) + col0;
;                 xv[(r + 1) & 1][0] = NTL(xr); xv[(r + 1) & 1][1] = NTL(xr + 4); xv[(r + 1) & 1][2] = NTL(xr + 128); xv[(r + 1) & 1][3] = NTL(xr + 132); }
;             float* hr = H + (size_t)row * DM + col0; float ss = 0.f;
; #pragma unroll
;             for (int bj = 0; bj < 2; ++bj) {
;                 f32x4 v0 = acc[ai][bj][m][0] + xv[r & 1][2 * bj], v1 = acc[ai][bj][m][1] + xv[r & 1][2 * bj + 1];
;                 NTS(v0, hr + bj * 128); NTS(v1, hr + bj * 128 + 4);
;                 u32x4 w; w.x = cvt_pk_bf16(v0[0], v0[1]); w.y = cvt_pk_bf16(v0[2], v0[3]); w.z = cvt_pk_bf16(v1[0], v1[1]); w.w = cvt_pk_bf16(v1[2], v1[3]);
;                 *(u32x4*)(HB + (size_t)row * DM + col0 + bj * 128) = w;
; #pragma unroll
;                 for (int j = 0; j < 4; ++j) ss += v0[j] * v0[j] + v1[j] * v1[j]; }
;             ss += __shfl_xor(ss, 16); ss += __shfl_xor(ss, 32);
;             if (fq == 0) unsafeAtomicAdd(rss + row, ss); __builtin_amdgcn_sched_barrier(0); }
	v_pk_add_f32 v[62:63], v[62:63], v[170:171]
	v_pk_add_f32 v[64:65], v[64:65], v[172:173]
	v_pk_add_f32 v[58:59], v[58:59], v[174:175]
	v_pk_add_f32 v[60:61], v[60:61], v[176:177]
	v_pk_add_f32 v[54:55], v[54:55], v[178:179]
	v_pk_add_f32 v[56:57], v[56:57], v[180:181]
	v_pk_add_f32 v[50:51], v[50:51], v[182:183]
	v_pk_add_f32 v[52:53], v[52:53], v[184:185]
	v_add_u32_e32 v228, 0x80000, v156
	v_add_u32_e32 v229, 0x40000, v157
	global_store_dwordx4 v228, v[62:65], s[22:23] nt
	global_store_dwordx4 v228, v[58:61], s[22:23] offset:16 nt
	global_store_dwordx4 v228, v[54:57], s[22:23] offset:512 nt
	global_store_dwordx4 v228, v[50:53], s[22:23] offset:528 nt
	v_cvt_pk_bf16_f32 v170, v62, v63
	v_cvt_pk_bf16_f32 v171, v64, v65
	v_cvt_pk_bf16_f32 v172, v58, v59
	v_cvt_pk_bf16_f32 v173, v60, v61
	v_cvt_pk_bf16_f32 v174, v54, v55
	v_cvt_pk_bf16_f32 v175, v56, v57
	v_cvt_pk_bf16_f32 v176, v50, v51
	v_cvt_pk_bf16_f32 v177, v52, v53
	global_store_dwordx4 v229, v[170:173], s[6:7]
	global_store_dwordx4 v229, v[174:177], s[6:7] offset:256
	v_pk_mul_f32 v[222:223], v[62:63], v[62:63]
	s_nop 0
	v_pk_fma_f32 v[222:223], v[64:65], v[64:65], v[222:223]
	s_nop 0
	v_pk_fma_f32 v[222:223], v[58:59], v[58:59], v[222:223]
	s_nop 0
	v_pk_fma_f32 v[222:223], v[60:61], v[60:61], v[222:223]
	s_nop 0
	v_pk_fma_f32 v[222:223], v[54:55], v[54:55], v[222:223]
	s_nop 0
	v_pk_fma_f32 v[222:223], v[56:57], v[56:57], v[222:223]
	s_nop 0
	v_pk_fma_f32 v[222:223], v[50:51], v[50:51], v[222:223]
	s_nop 0
	v_pk_fma_f32 v[222:223], v[52:53], v[52:53], v[222:223]
	s_nop 1
	v_add_u32_e32 v227, 0xb0000, v156
	global_load_dwordx4 v[170:173], v227, s[60:61] nt
	global_load_dwordx4 v[174:177], v227, s[60:61] offset:16 nt
	global_load_dwordx4 v[178:181], v227, s[60:61] offset:512 nt
	global_load_dwordx4 v[182:185], v227, s[60:61] offset:528 nt
	s_nop 0
	v_add_f32_e32 v222, v222, v223
	ds_bpermute_b32 v224, v159, v222
	ds_bpermute_b32 v225, v160, v222
	ds_bpermute_b32 v226, v161, v222
	s_waitcnt lgkmcnt(0)
	v_add_f32_e32 v222, v222, v224
	v_add_f32_e32 v225, v225, v226
	v_add_f32_e32 v222, v222, v225
	s_mov_b64 s[16:17], exec
	s_and_b64 exec, exec, s[42:43]
	global_atomic_add_f32 v158, v222, s[8:9] offset:512
	s_mov_b64 exec, s[16:17]
	s_waitcnt vmcnt(23)
	v_pk_add_f32 v[46:47], v[46:47], v[188:189]
	v_pk_add_f32 v[48:49], v[48:49], v[190:191]
	v_pk_add_f32 v[42:43], v[42:43], v[192:193]
	v_pk_add_f32 v[44:45], v[44:45], v[194:195]
	v_pk_add_f32 v[38:39], v[38:39], v[196:197]
	v_pk_add_f32 v[40:41], v[40:41], v[198:199]
	v_pk_add_f32 v[34:35], v[34:35], v[204:205]
	v_pk_add_f32 v[36:37], v[36:37], v[206:207]
	v_add_u32_e32 v228, 0x90000, v156
	v_add_u32_e32 v229, 0x48000, v157
	global_store_dwordx4 v228, v[46:49], s[22:23] nt
	global_store_dwordx4 v228, v[42:45], s[22:23] offset:16 nt
	global_store_dwordx4 v228, v[38:41], s[22:23] offset:512 nt
	global_store_dwordx4 v228, v[34:37], s[22:23] offset:528 nt
	v_cvt_pk_bf16_f32 v188, v46, v47
	v_cvt_pk_bf16_f32 v189, v48, v49
	v_cvt_pk_bf16_f32 v190, v42, v43
	v_cvt_pk_bf16_f32 v191, v44, v45
	v_cvt_pk_bf16_f32 v192, v38, v39
	v_cvt_pk_bf16_f32 v193, v40, v41
	v_cvt_pk_bf16_f32 v194, v34, v35
	v_cvt_pk_bf16_f32 v195, v36, v37
	global_store_dwordx4 v229, v[188:191], s[6:7]
	global_store_dwordx4 v229, v[192:195], s[6:7] offset:256
	v_pk_mul_f32 v[222:223], v[46:47], v[46:47]
	s_nop 0
	v_pk_fma_f32 v[222:223], v[48:49], v[48:49], v[222:223]
	s_nop 0
	v_pk_fma_f32 v[222:223], v[42:43], v[42:43], v[222:223]
	s_nop 0
	v_pk_fma_f32 v[222:223], v[44:45], v[44:45], v[222:223]
	s_nop 0
	v_pk_fma_f32 v[222:223], v[38:39], v[38:39], v[222:223]
	s_nop 0
	v_pk_fma_f32 v[222:223], v[40:41], v[40:41], v[222:223]
	s_nop 0
	v_pk_fma_f32 v[222:223], v[34:35], v[34:35], v[222:223]
	s_nop 0
	v_pk_fma_f32 v[222:223], v[36:37], v[36:37], v[222:223]
	s_nop 0
	v_add_f32_e32 v222, v222, v223
	ds_bpermute_b32 v224, v159, v222
	ds_bpermute_b32 v225, v160, v222
	ds_bpermute_b32 v226, v161, v222
	s_waitcnt lgkmcnt(0)
	v_add_f32_e32 v222, v222, v224
	v_add_f32_e32 v225, v225, v226
	v_add_f32_e32 v222, v222, v225
	s_mov_b64 s[16:17], exec
	s_and_b64 exec, exec, s[42:43]
	global_atomic_add_f32 v158, v222, s[8:9] offset:576
	s_mov_b64 exec, s[16:17]
	s_waitcnt vmcnt(19)
; #define NTL(p) __builtin_nontemporal_load((const f32x4*)(p))
; #define NTS(v, p) __builtin_nontemporal_store((v), (f32x4*)(p))
; __device__ __forceinline__ unsigned cvt_pk_bf16(float lo, float hi) { unsigned r; asm volatile("v_cvt_pk_bf16_f32 %0, %1, %2" : "=v"(r) : "v"(lo), "v"(hi)); return r; }
;     __device__ __forceinline__ void operator()(AccT& acc, const Unit& u, int wr, int wc, int fr, int fq) const {
;     ...
;         for (int r = 0; r < 8; ++r) { const int ai = r >> 2, m = r & 3; const int row = row0 + ai * 128 + m * 16;
;             if (r < 7) { const int rn = row0 + ((r + 1) >> 2) * 128 + ((r + 1) & 3) * 16; const float* xr = (rn < HALF_TOK ? x0 + (size_t)rn * DM : x1 + (size_t)(rn - HALF_TOK) * DM) + col0;
;                 xv[(r + 1) & 1][0] = NTL(xr); xv[(r + 1) & 1][1] = NTL(xr + 4); xv[(r + 1) & 1][2] = NTL(xr + 128); xv[(r + 1) & 1][3] = NTL(xr + 132); }
;             float* hr = H + (size_t)row * DM + col0; float ss = 0.f;
; #pragma unroll
;             for (int bj = 0; bj < 2; ++bj) {
;                 f32x4 v0 = acc[ai][bj][m][0] + xv[r & 1][2 * bj], v1 = acc[ai][bj][m][1] + xv[r & 1][2 * bj + 1];
;                 NTS(v0, hr + bj * 128); NTS(v1, hr + bj * 128 + 4);
;                 u32x4 w; w.x = cvt_pk_bf16(v0[0], v0[1]); w.y = cvt_pk_bf16(v0[2], v0[3]); w.z = cvt_pk_bf16(v1[0], v1[1]); w.w = cvt_pk_bf16(v1[2], v1[3]);
;                 *(u32x4*)(HB + (size_t)row * DM + col0 + bj * 128) = w;
; #pragma unroll
;                 for (int j = 0; j < 4; ++j) ss += v0[j] * v0[j] + v1[j] * v1[j]; }
;             ss += __shfl_xor(ss, 16); ss += __shfl_xor(ss, 32);
;             if (fq == 0) unsafeAtomicAdd(rss + row, ss); __builtin_amdgcn_sched_barrier(0); }
	v_pk_add_f32 v[30:31], v[30:31], v[130:131]
	v_pk_add_f32 v[32:33], v[32:33], v[132:133]
	v_pk_add_f32 v[26:27], v[26:27], v[134:135]
	v_pk_add_f32 v[28:29], v[28:29], v[136:137]
	v_pk_add_f32 v[22:23], v[22:23], v[138:139]
	v_pk_add_f32 v[24:25], v[24:25], v[140:141]
	v_pk_add_f32 v[18:19], v[18:19], v[142:143]
	v_pk_add_f32 v[20:21], v[20:21], v[144:145]
	v_add_u32_e32 v228, 0xa0000, v156
	v_add_u32_e32 v229, 0x50000, v157
	global_store_dwordx4 v228, v[30:33], s[22:23] nt
	global_store_dwordx4 v228, v[26:29], s[22:23] offset:16 nt
	global_store_dwordx4 v228, v[22:25], s[22:23] offset:512 nt
	global_store_dwordx4 v228, v[18:21], s[22:23] offset:528 nt
	v_cvt_pk_bf16_f32 v130, v30, v31
	v_cvt_pk_bf16_f32 v131, v32, v33
	v_cvt_pk_bf16_f32 v132, v26, v27
	v_cvt_pk_bf16_f32 v133, v28, v29
	v_cvt_pk_bf16_f32 v134, v22, v23
	v_cvt_pk_bf16_f32 v135, v24, v25
	v_cvt_pk_bf16_f32 v136, v18, v19
	v_cvt_pk_bf16_f32 v137, v20, v21
	global_store_dwordx4 v229, v[130:133], s[6:7]
	global_store_dwordx4 v229, v[134:137], s[6:7] offset:256
	v_pk_mul_f32 v[222:223], v[30:31], v[30:31]
	s_nop 0
	v_pk_fma_f32 v[222:223], v[32:33], v[32:33], v[222:223]
	s_nop 0
	v_pk_fma_f32 v[222:223], v[26:27], v[26:27], v[222:223]
	s_nop 0
	v_pk_fma_f32 v[222:223], v[28:29], v[28:29], v[222:223]
	s_nop 0
	v_pk_fma_f32 v[222:223], v[22:23], v[22:23], v[222:223]
	s_nop 0
	v_pk_fma_f32 v[222:223], v[24:25], v[24:25], v[222:223]
	s_nop 0
	v_pk_fma_f32 v[222:223], v[18:19], v[18:19], v[222:223]
	s_nop 0
	v_pk_fma_f32 v[222:223], v[20:21], v[20:21], v[222:223]
	s_nop 0
	v_add_f32_e32 v222, v222, v223
	ds_bpermute_b32 v224, v159, v222
	ds_bpermute_b32 v225, v160, v222
	ds_bpermute_b32 v226, v161, v222
	s_waitcnt lgkmcnt(0)
	v_add_f32_e32 v222, v222, v224
	v_add_f32_e32 v225, v225, v226
	v_add_f32_e32 v222, v222, v225
	s_mov_b64 s[16:17], exec
	s_and_b64 exec, exec, s[42:43]
	global_atomic_add_f32 v158, v222, s[8:9] offset:640
	s_mov_b64 exec, s[16:17]
	s_waitcnt vmcnt(15)
	v_pk_add_f32 v[14:15], v[14:15], v[170:171]
	v_pk_add_f32 v[16:17], v[16:17], v[172:173]
	v_pk_add_f32 v[10:11], v[10:11], v[174:175]
	v_pk_add_f32 v[12:13], v[12:13], v[176:177]
	v_pk_add_f32 v[6:7], v[6:7], v[178:179]
	v_pk_add_f32 v[8:9], v[8:9], v[180:181]
	v_pk_add_f32 v[2:3], v[2:3], v[182:183]
	v_pk_add_f32 v[4:5], v[4:5], v[184:185]
	v_add_u32_e32 v228, 0xb0000, v156
	v_add_u32_e32 v229, 0x58000, v157
	global_store_dwordx4 v228, v[14:17], s[22:23] nt
	global_store_dwordx4 v228, v[10:13], s[22:23] offset:16 nt
	global_store_dwordx4 v228, v[6:9], s[22:23] offset:512 nt
	global_store_dwordx4 v228, v[2:5], s[22:23] offset:528 nt
	v_cvt_pk_bf16_f32 v170, v14, v15
	v_cvt_pk_bf16_f32 v171, v16, v17
	v_cvt_pk_bf16_f32 v172, v10, v11
	v_cvt_pk_bf16_f32 v173, v12, v13
	v_cvt_pk_bf16_f32 v174, v6, v7
	v_cvt_pk_bf16_f32 v175, v8, v9
	v_cvt_pk_bf16_f32 v176, v2, v3
	v_cvt_pk_bf16_f32 v177, v4, v5
	global_store_dwordx4 v229, v[170:173], s[6:7]
	global_store_dwordx4 v229, v[174:177], s[6:7] offset:256
	v_pk_mul_f32 v[222:223], v[14:15], v[14:15]
	s_nop 0
	v_pk_fma_f32 v[222:223], v[16:17], v[16:17], v[222:223]
	s_nop 0
	v_pk_fma_f32 v[222:223], v[10:11], v[10:11], v[222:223]
	s_nop 0
	v_pk_fma_f32 v[222:223], v[12:13], v[12:13], v[222:223]
	s_nop 0
	v_pk_fma_f32 v[222:223], v[6:7], v[6:7], v[222:223]
	s_nop 0
	v_pk_fma_f32 v[222:223], v[8:9], v[8:9], v[222:223]
	s_nop 0
	v_pk_fma_f32 v[222:223], v[2:3], v[2:3], v[222:223]
	s_nop 0
	v_pk_fma_f32 v[222:223], v[4:5], v[4:5], v[222:223]
	s_nop 0
	v_add_f32_e32 v222, v222, v223
	ds_bpermute_b32 v224, v159, v222
	ds_bpermute_b32 v225, v160, v222
	ds_bpermute_b32 v226, v161, v222
	s_waitcnt lgkmcnt(0)
	v_add_f32_e32 v222, v222, v224
	v_add_f32_e32 v225, v225, v226
	v_add_f32_e32 v222, v222, v225
	s_mov_b64 s[16:17], exec
	s_and_b64 exec, exec, s[42:43]
	global_atomic_add_f32 v158, v222, s[8:9] offset:704
	s_mov_b64 exec, s[16:17]
	v_readlane_b32 s60, v254, 34
	v_readlane_b32 s61, v254, 35
	v_readlane_b32 s62, v254, 36
	v_readlane_b32 s63, v254, 37
	v_readlane_b32 s64, v254, 38
	v_readlane_b32 s65, v254, 39
	v_readlane_b32 s66, v254, 40
	v_readlane_b32 s67, v254, 41
	v_readlane_b32 s68, v254, 42
	v_readlane_b32 s69, v254, 43
	v_readlane_b32 s70, v254, 44
	v_readlane_b32 s71, v254, 45
	v_readlane_b32 s72, v254, 46
	v_readlane_b32 s73, v254, 47
	v_readlane_b32 s74, v254, 48
	v_readlane_b32 s75, v254, 49
	s_mov_b64 s[16:17], 0
	s_branch .LBB0_34

; #define NTL(p) __builtin_nontemporal_load((const f32x4*)(p))
; #define NTS(v, p) __builtin_nontemporal_store((v), (f32x4*)(p))
; __device__ __forceinline__ unsigned cvt_pk_bf16(float lo, float hi) { unsigned r; asm volatile("v_cvt_pk_bf16_f32 %0, %1, %2" : "=v"(r) : "v"(lo), "v"(hi)); return r; }
;     __device__ __forceinline__ void operator()(AccT& acc, const Unit& u, int wr, int wc, int fr, int fq) const {
;     ...
;         const int row0 = half * HALF_TOK + u.pm * 256 + wr * 64 + fr, col0 = u.pn * 256 + wc * 32 + 8 * fq;
;         f32x4 hv[2][4];
;         { const float* hr = H + (size_t)row0 * DM + col0; hv[0][0] = NTL(hr); hv[0][1] = NTL(hr + 4); hv[0][2] = NTL(hr + 128); hv[0][3] = NTL(hr + 132); }
; #pragma unroll
;         for (int r = 0; r < 8; ++r) { const int ai = r >> 2, m = r & 3; const int row = row0 + ai * 128 + m * 16;
;             if (r < 7) { const int rn = row0 + ((r + 1) >> 2) * 128 + ((r + 1) & 3) * 16; const float* hn = H + (size_t)rn * DM + col0;
;                 hv[(r + 1) & 1][0] = NTL(hn); hv[(r + 1) & 1][1] = NTL(hn + 4); hv[(r + 1) & 1][2] = NTL(hn + 128); hv[(r + 1) & 1][3] = NTL(hn + 132); }
;             float* hr = H + (size_t)row * DM + col0; float ss = 0.f;
; #pragma unroll
;             for (int bj = 0; bj < 2; ++bj) {
;                 f32x4 v0 = acc[ai][bj][m][0] + hv[r & 1][2 * bj], v1 = acc[ai][bj][m][1] + hv[r & 1][2 * bj + 1];
;                 NTS(v0, hr + bj * 128); NTS(v1, hr + bj * 128 + 4);
;                 u32x4 w; w.x = cvt_pk_bf16(v0[0], v0[1]); w.y = cvt_pk_bf16(v0[2], v0[3]); w.z = cvt_pk_bf16(v1[0], v1[1]); w.w = cvt_pk_bf16(v1[2], v1[3]);
;                 *(u32x4*)(HB + (size_t)row * DM + col0 + bj * 128) = w;
; #pragma unroll
;                 for (int j = 0; j < 4; ++j) ss += v0[j] * v0[j] + v1[j] * v1[j]; }
;             ss += __shfl_xor(ss, 16); ss += __shfl_xor(ss, 32);
;             if (fq == 0) unsafeAtomicAdd(rss + row, ss); __builtin_amdgcn_sched_barrier(0); }
.LBB0_851:
	s_lshl_b32 s16, s75, 8
	s_add_i32 s16, s57, s16
	v_add_u32_e32 v224, s16, v164
	s_lshl_b32 s16, s76, 8
	s_or_b32 s16, s16, s54
	v_lshl_add_u32 v225, v165, 3, s16
	v_lshlrev_b32_e32 v158, 2, v224
	v_lshlrev_b32_e32 v225, 2, v225
	v_lshl_add_u32 v156, v224, 12, v225
	v_lshrrev_b32_e32 v157, 1, v156
	v_xor_b32_e32 v159, 16, v203
	v_xor_b32_e32 v160, 32, v203
	v_xor_b32_e32 v161, 48, v203
	v_lshlrev_b32_e32 v159, 2, v159
	v_lshlrev_b32_e32 v160, 2, v160
	v_lshlrev_b32_e32 v161, 2, v161
	v_cmp_eq_u32_e64 s[42:43], 0, v165
	global_load_dwordx4 v[130:133], v156, s[22:23] nt
	global_load_dwordx4 v[134:137], v156, s[22:23] offset:16 nt
	global_load_dwordx4 v[138:141], v156, s[22:23] offset:512 nt
	global_load_dwordx4 v[142:145], v156, s[22:23] offset:528 nt
	v_add_u32_e32 v227, 0x10000, v156
	global_load_dwordx4 v[170:173], v227, s[22:23] nt
	global_load_dwordx4 v[174:177], v227, s[22:23] offset:16 nt
	global_load_dwordx4 v[178:181], v227, s[22:23] offset:512 nt
	global_load_dwordx4 v[182:185], v227, s[22:23] offset:528 nt
	v_add_u32_e32 v227, 0x20000, v156
	global_load_dwordx4 v[188:191], v227, s[22:23] nt
	global_load_dwordx4 v[192:195], v227, s[22:23] offset:16 nt
	global_load_dwordx4 v[196:199], v227, s[22:23] offset:512 nt
	global_load_dwordx4 v[204:207], v227, s[22:23] offset:528 nt
	s_waitcnt vmcnt(8)
	v_pk_add_f32 v[122:123], v[122:123], v[130:131]
	v_pk_add_f32 v[124:125], v[124:125], v[132:133]
	v_pk_add_f32 v[126:127], v[126:127], v[134:135]
	v_pk_add_f32 v[128:129], v[128:129], v[136:137]
	v_pk_add_f32 v[118:119], v[118:119], v[138:139]
	v_pk_add_f32 v[120:121], v[120:121], v[140:141]
	v_pk_add_f32 v[114:115], v[114:115], v[142:143]
	v_pk_add_f32 v[116:117], v[116:117], v[144:145]
	global_store_dwordx4 v156, v[122:125], s[22:23] nt
	global_store_dwordx4 v156, v[126:129], s[22:23] offset:16 nt
	global_store_dwordx4 v156, v[118:121], s[22:23] offset:512 nt
	global_store_dwordx4 v156, v[114:117], s[22:23] offset:528 nt
	v_cvt_pk_bf16_f32 v130, v122, v123
	v_cvt_pk_bf16_f32 v131, v124, v125
	v_cvt_pk_bf16_f32 v132, v126, v127
	v_cvt_pk_bf16_f32 v133, v128, v129
	v_cvt_pk_bf16_f32 v134, v118, v119
	v_cvt_pk_bf16_f32 v135, v120, v121
	v_cvt_pk_bf16_f32 v136, v114, v115
	v_cvt_pk_bf16_f32 v137, v116, v117
	global_store_dwordx4 v157, v[130:133], s[2:3]
	global_store_dwordx4 v157, v[134:137], s[2:3] offset:256
	v_pk_mul_f32 v[222:223], v[122:123], v[122:123]
	s_nop 0
	v_pk_fma_f32 v[222:223], v[124:125], v[124:125], v[222:223]
	s_nop 0
	v_pk_fma_f32 v[222:223], v[126:127], v[126:127], v[222:223]
	s_nop 0
	v_pk_fma_f32 v[222:223], v[128:129], v[128:129], v[222:223]
	s_nop 0
	v_pk_fma_f32 v[222:223], v[118:119], v[118:119], v[222:223]
	s_nop 0
	v_pk_fma_f32 v[222:223], v[120:121], v[120:121], v[222:223]
	s_nop 0
	v_pk_fma_f32 v[222:223], v[114:115], v[114:115], v[222:223]
	s_nop 0
	v_pk_fma_f32 v[222:223], v[116:117], v[116:117], v[222:223]
	s_nop 1
	v_add_u32_e32 v227, 0x30000, v156
	global_load_dwordx4 v[130:133], v227, s[22:23] nt
	global_load_dwordx4 v[134:137], v227, s[22:23] offset:16 nt
	global_load_dwordx4 v[138:141], v227, s[22:23] offset:512 nt
	global_load_dwordx4 v[142:145], v227, s[22:23] offset:528 nt
	s_nop 0
	v_add_f32_e32 v222, v222, v223
	ds_bpermute_b32 v224, v159, v222
	ds_bpermute_b32 v225, v160, v222
	ds_bpermute_b32 v226, v161, v222
	s_waitcnt lgkmcnt(0)
	v_add_f32_e32 v222, v222, v224
	v_add_f32_e32 v225, v225, v226
	v_add_f32_e32 v222, v222, v225
	s_mov_b64 s[16:17], exec
	s_and_b64 exec, exec, s[42:43]
	global_atomic_add_f32 v158, v222, s[8:9]
	s_mov_b64 exec, s[16:17]
	s_waitcnt vmcnt(15)
	v_pk_add_f32 v[110:111], v[110:111], v[170:171]
	v_pk_add_f32 v[112:113], v[112:113], v[172:173]
	v_pk_add_f32 v[106:107], v[106:107], v[174:175]
	v_pk_add_f32 v[108:109], v[108:109], v[176:177]
	v_pk_add_f32 v[102:103], v[102:103], v[178:179]
	v_pk_add_f32 v[104:105], v[104:105], v[180:181]
	v_pk_add_f32 v[98:99], v[98:99], v[182:183]
	v_pk_add_f32 v[100:101], v[100:101], v[184:185]
	v_add_u32_e32 v228, 0x10000, v156
	v_add_u32_e32 v229, 0x8000, v157
	global_store_dwordx4 v228, v[110:113], s[22:23] nt
	global_store_dwordx4 v228, v[106:109], s[22:23] offset:16 nt
	global_store_dwordx4 v228, v[102:105], s[22:23] offset:512 nt
	global_store_dwordx4 v228, v[98:101], s[22:23] offset:528 nt
	v_cvt_pk_bf16_f32 v170, v110, v111
	v_cvt_pk_bf16_f32 v171, v112, v113
	v_cvt_pk_bf16_f32 v172, v106, v107
	v_cvt_pk_bf16_f32 v173, v108, v109
	v_cvt_pk_bf16_f32 v174, v102, v103
	v_cvt_pk_bf16_f32 v175, v104, v105
	v_cvt_pk_bf16_f32 v176, v98, v99
	v_cvt_pk_bf16_f32 v177, v100, v101
	global_store_dwordx4 v229, v[170:173], s[2:3]
	global_store_dwordx4 v229, v[174:177], s[2:3] offset:256
	v_pk_mul_f32 v[222:223], v[110:111], v[110:111]
	s_nop 0
	v_pk_fma_f32 v[222:223], v[112:113], v[112:113], v[222:223]
	s_nop 0
	v_pk_fma_f32 v[222:223], v[106:107], v[106:107], v[222:223]
	s_nop 0
	v_pk_fma_f32 v[222:223], v[108:109], v[108:109], v[222:223]
	s_nop 0
	v_pk_fma_f32 v[222:223], v[102:103], v[102:103], v[222:223]
	s_nop 0
	v_pk_fma_f32 v[222:223], v[104:105], v[104:105], v[222:223]
	s_nop 0
	v_pk_fma_f32 v[222:223], v[98:99], v[98:99], v[222:223]
	s_nop 0
	v_pk_fma_f32 v[222:223], v[100:101], v[100:101], v[222:223]
	s_nop 1
	v_add_u32_e32 v227, 0x80000, v156
	global_load_dwordx4 v[170:173], v227, s[22:23] nt
	global_load_dwordx4 v[174:177], v227, s[22:23] offset:16 nt
	global_load_dwordx4 v[178:181], v227, s[22:23] offset:512 nt
	global_load_dwordx4 v[182:185], v227, s[22:23] offset:528 nt
	s_nop 0
	v_add_f32_e32 v222, v222, v223
	ds_bpermute_b32 v224, v159, v222
	ds_bpermute_b32 v225, v160, v222
	ds_bpermute_b32 v226, v161, v222
	s_waitcnt lgkmcnt(0)
; #define NTL(p) __builtin_nontemporal_load((const f32x4*)(p))
; #define NTS(v, p) __builtin_nontemporal_store((v), (f32x4*)(p))
; __device__ __forceinline__ unsigned cvt_pk_bf16(float lo, float hi) { unsigned r; asm volatile("v_cvt_pk_bf16_f32 %0, %1, %2" : "=v"(r) : "v"(lo), "v"(hi)); return r; }
;     __device__ __forceinline__ void operator()(AccT& acc, const Unit& u, int wr, int wc, int fr, int fq) const {
;     ...
;         const int row0 = half * HALF_TOK + u.pm * 256 + wr * 64 + fr, col0 = u.pn * 256 + wc * 32 + 8 * fq;
;         f32x4 hv[2][4];
;         { const float* hr = H + (size_t)row0 * DM + col0; hv[0][0] = NTL(hr); hv[0][1] = NTL(hr + 4); hv[0][2] = NTL(hr + 128); hv[0][3] = NTL(hr + 132); }
; #pragma unroll
;         for (int r = 0; r < 8; ++r) { const int ai = r >> 2, m = r & 3; const int row = row0 + ai * 128 + m * 16;
;             if (r < 7) { const int rn = row0 + ((r + 1) >> 2) * 128 + ((r + 1) & 3) * 16; const float* hn = H + (size_t)rn * DM + col0;
;                 hv[(r + 1) & 1][0] = NTL(hn); hv[(r + 1) & 1][1] = NTL(hn + 4); hv[(r + 1) & 1][2] = NTL(hn + 128); hv[(r + 1) & 1][3] = NTL(hn + 132); }
;             float* hr = H + (size_t)row * DM + col0; float ss = 0.f;
; #pragma unroll
;             for (int bj = 0; bj < 2; ++bj) {
;                 f32x4 v0 = acc[ai][bj][m][0] + hv[r & 1][2 * bj], v1 = acc[ai][bj][m][1] + hv[r & 1][2 * bj + 1];
;                 NTS(v0, hr + bj * 128); NTS(v1, hr + bj * 128 + 4);
;                 u32x4 w; w.x = cvt_pk_bf16(v0[0], v0[1]); w.y = cvt_pk_bf16(v0[2], v0[3]); w.z = cvt_pk_bf16(v1[0], v1[1]); w.w = cvt_pk_bf16(v1[2], v1[3]);
;                 *(u32x4*)(HB + (size_t)row * DM + col0 + bj * 128) = w;
; #pragma unroll
;                 for (int j = 0; j < 4; ++j) ss += v0[j] * v0[j] + v1[j] * v1[j]; }
;             ss += __shfl_xor(ss, 16); ss += __shfl_xor(ss, 32);
;             if (fq == 0) unsafeAtomicAdd(rss + row, ss); __builtin_amdgcn_sched_barrier(0); }
	v_add_f32_e32 v222, v222, v224
	v_add_f32_e32 v225, v225, v226
	v_add_f32_e32 v222, v222, v225
	s_mov_b64 s[16:17], exec
	s_and_b64 exec, exec, s[42:43]
	global_atomic_add_f32 v158, v222, s[8:9] offset:64
	s_mov_b64 exec, s[16:17]
	s_waitcnt vmcnt(22)
	v_pk_add_f32 v[94:95], v[94:95], v[188:189]
	v_pk_add_f32 v[96:97], v[96:97], v[190:191]
	v_pk_add_f32 v[90:91], v[90:91], v[192:193]
	v_pk_add_f32 v[92:93], v[92:93], v[194:195]
	v_pk_add_f32 v[86:87], v[86:87], v[196:197]
	v_pk_add_f32 v[88:89], v[88:89], v[198:199]
	v_pk_add_f32 v[82:83], v[82:83], v[204:205]
	v_pk_add_f32 v[84:85], v[84:85], v[206:207]
	v_add_u32_e32 v228, 0x20000, v156
	v_add_u32_e32 v229, 0x10000, v157
	global_store_dwordx4 v228, v[94:97], s[22:23] nt
	global_store_dwordx4 v228, v[90:93], s[22:23] offset:16 nt
	global_store_dwordx4 v228, v[86:89], s[22:23] offset:512 nt
	global_store_dwordx4 v228, v[82:85], s[22:23] offset:528 nt
	v_cvt_pk_bf16_f32 v188, v94, v95
	v_cvt_pk_bf16_f32 v189, v96, v97
	v_cvt_pk_bf16_f32 v190, v90, v91
	v_cvt_pk_bf16_f32 v191, v92, v93
	v_cvt_pk_bf16_f32 v192, v86, v87
	v_cvt_pk_bf16_f32 v193, v88, v89
	v_cvt_pk_bf16_f32 v194, v82, v83
	v_cvt_pk_bf16_f32 v195, v84, v85
	global_store_dwordx4 v229, v[188:191], s[2:3]
	global_store_dwordx4 v229, v[192:195], s[2:3] offset:256
	v_pk_mul_f32 v[222:223], v[94:95], v[94:95]
	s_nop 0
	v_pk_fma_f32 v[222:223], v[96:97], v[96:97], v[222:223]
	s_nop 0
	v_pk_fma_f32 v[222:223], v[90:91], v[90:91], v[222:223]
	s_nop 0
	v_pk_fma_f32 v[222:223], v[92:93], v[92:93], v[222:223]
	s_nop 0
	v_pk_fma_f32 v[222:223], v[86:87], v[86:87], v[222:223]
	s_nop 0
	v_pk_fma_f32 v[222:223], v[88:89], v[88:89], v[222:223]
	s_nop 0
	v_pk_fma_f32 v[222:223], v[82:83], v[82:83], v[222:223]
	s_nop 0
	v_pk_fma_f32 v[222:223], v[84:85], v[84:85], v[222:223]
	s_nop 1
	v_add_u32_e32 v227, 0x90000, v156
	global_load_dwordx4 v[188:191], v227, s[22:23] nt
	global_load_dwordx4 v[192:195], v227, s[22:23] offset:16 nt
	global_load_dwordx4 v[196:199], v227, s[22:23] offset:512 nt
	global_load_dwordx4 v[204:207], v227, s[22:23] offset:528 nt
	s_nop 0
	v_add_f32_e32 v222, v222, v223
	ds_bpermute_b32 v224, v159, v222
	ds_bpermute_b32 v225, v160, v222
	ds_bpermute_b32 v226, v161, v222
	s_waitcnt lgkmcnt(0)
	v_add_f32_e32 v222, v222, v224
	v_add_f32_e32 v225, v225, v226
	v_add_f32_e32 v222, v222, v225
	s_mov_b64 s[16:17], exec
	s_and_b64 exec, exec, s[42:43]
	global_atomic_add_f32 v158, v222, s[8:9] offset:128
	s_mov_b64 exec, s[16:17]
	s_waitcnt vmcnt(23)
	v_pk_add_f32 v[78:79], v[78:79], v[130:131]
	v_pk_add_f32 v[80:81], v[80:81], v[132:133]
	v_pk_add_f32 v[74:75], v[74:75], v[134:135]
	v_pk_add_f32 v[76:77], v[76:77], v[136:137]
	v_pk_add_f32 v[70:71], v[70:71], v[138:139]
	v_pk_add_f32 v[72:73], v[72:73], v[140:141]
	v_pk_add_f32 v[66:67], v[66:67], v[142:143]
	v_pk_add_f32 v[68:69], v[68:69], v[144:145]
	v_add_u32_e32 v228, 0x30000, v156
	v_add_u32_e32 v229, 0x18000, v157
	global_store_dwordx4 v228, v[78:81], s[22:23] nt
	global_store_dwordx4 v228, v[74:77], s[22:23] offset:16 nt
	global_store_dwordx4 v228, v[70:73], s[22:23] offset:512 nt
	global_store_dwordx4 v228, v[66:69], s[22:23] offset:528 nt
	v_cvt_pk_bf16_f32 v130, v78, v79
	v_cvt_pk_bf16_f32 v131, v80, v81
	v_cvt_pk_bf16_f32 v132, v74, v75
	v_cvt_pk_bf16_f32 v133, v76, v77
	v_cvt_pk_bf16_f32 v134, v70, v71
	v_cvt_pk_bf16_f32 v135, v72, v73
	v_cvt_pk_bf16_f32 v136, v66, v67
	v_cvt_pk_bf16_f32 v137, v68, v69
	global_store_dwordx4 v229, v[130:133], s[2:3]
	global_store_dwordx4 v229, v[134:137], s[2:3] offset:256
	v_pk_mul_f32 v[222:223], v[78:79], v[78:79]
	s_nop 0
	v_pk_fma_f32 v[222:223], v[80:81], v[80:81], v[222:223]
	s_nop 0
	v_pk_fma_f32 v[222:223], v[74:75], v[74:75], v[222:223]
	s_nop 0
	v_pk_fma_f32 v[222:223], v[76:77], v[76:77], v[222:223]
	s_nop 0
	v_pk_fma_f32 v[222:223], v[70:71], v[70:71], v[222:223]
	s_nop 0
	v_pk_fma_f32 v[222:223], v[72:73], v[72:73], v[222:223]
	s_nop 0
	v_pk_fma_f32 v[222:223], v[66:67], v[66:67], v[222:223]
	s_nop 0
	v_pk_fma_f32 v[222:223], v[68:69], v[68:69], v[222:223]
	s_nop 1
	v_add_u32_e32 v227, 0xa0000, v156
	global_load_dwordx4 v[130:133], v227, s[22:23] nt
	global_load_dwordx4 v[134:137], v227, s[22:23] offset:16 nt
	global_load_dwordx4 v[138:141], v227, s[22:23] offset:512 nt
	global_load_dwordx4 v[142:145], v227, s[22:23] offset:528 nt
	s_nop 0
	v_add_f32_e32 v222, v222, v223
	ds_bpermute_b32 v224, v159, v222
	ds_bpermute_b32 v225, v160, v222
	ds_bpermute_b32 v226, v161, v222
	s_waitcnt lgkmcnt(0)
	v_add_f32_e32 v222, v222, v224
	v_add_f32_e32 v225, v225, v226
	v_add_f32_e32 v222, v222, v225
	s_mov_b64 s[16:17], exec
	s_and_b64 exec, exec, s[42:43]
	global_atomic_add_f32 v158, v222, s[8:9] offset:192
	s_mov_b64 exec, s[16:17]
	s_waitcnt vmcnt(23)
; #define NTL(p) __builtin_nontemporal_load((const f32x4*)(p))
; #define NTS(v, p) __builtin_nontemporal_store((v), (f32x4*)(p))
; __device__ __forceinline__ unsigned cvt_pk_bf16(float lo, float hi) { unsigned r; asm volatile("v_cvt_pk_bf16_f32 %0, %1, %2" : "=v"(r) : "v"(lo), "v"(hi)); return r; }
;     __device__ __forceinline__ void operator()(AccT& acc, const Unit& u, int wr, int wc, int fr, int fq) const {
;     ...
;         const int row0 = half * HALF_TOK + u.pm * 256 + wr * 64 + fr, col0 = u.pn * 256 + wc * 32 + 8 * fq;
;         f32x4 hv[2][4];
;         { const float* hr = H + (size_t)row0 * DM + col0; hv[0][0] = NTL(hr); hv[0][1] = NTL(hr + 4); hv[0][2] = NTL(hr + 128); hv[0][3] = NTL(hr + 132); }
; #pragma unroll
;         for (int r = 0; r < 8; ++r) { const int ai = r >> 2, m = r & 3; const int row = row0 + ai * 128 + m * 16;
;             if (r < 7) { const int rn = row0 + ((r + 1) >> 2) * 128 + ((r + 1) & 3) * 16; const float* hn = H + (size_t)rn * DM + col0;
;                 hv[(r + 1) & 1][0] = NTL(hn); hv[(r + 1) & 1][1] = NTL(hn + 4); hv[(r + 1) & 1][2] = NTL(hn + 128); hv[(r + 1) & 1][3] = NTL(hn + 132); }
;             float* hr = H + (size_t)row * DM + col0; float ss = 0.f;
; #pragma unroll
;             for (int bj = 0; bj < 2; ++bj) {
;                 f32x4 v0 = acc[ai][bj][m][0] + hv[r & 1][2 * bj], v1 = acc[ai][bj][m][1] + hv[r & 1][2 * bj + 1];
;                 NTS(v0, hr + bj * 128); NTS(v1, hr + bj * 128 + 4);
;                 u32x4 w; w.x = cvt_pk_bf16(v0[0], v0[1]); w.y = cvt_pk_bf16(v0[2], v0[3]); w.z = cvt_pk_bf16(v1[0], v1[1]); w.w = cvt_pk_bf16(v1[2], v1[3]);
;                 *(u32x4*)(HB + (size_t)row * DM + col0 + bj * 128) = w;
; #pragma unroll
;                 for (int j = 0; j < 4; ++j) ss += v0[j] * v0[j] + v1[j] * v1[j]; }
;             ss += __shfl_xor(ss, 16); ss += __shfl_xor(ss, 32);
;             if (fq == 0) unsafeAtomicAdd(rss + row, ss); __builtin_amdgcn_sched_barrier(0); }
	v_pk_add_f32 v[62:63], v[62:63], v[170:171]
	v_pk_add_f32 v[64:65], v[64:65], v[172:173]
	v_pk_add_f32 v[58:59], v[58:59], v[174:175]
	v_pk_add_f32 v[60:61], v[60:61], v[176:177]
	v_pk_add_f32 v[54:55], v[54:55], v[178:179]
	v_pk_add_f32 v[56:57], v[56:57], v[180:181]
	v_pk_add_f32 v[50:51], v[50:51], v[182:183]
	v_pk_add_f32 v[52:53], v[52:53], v[184:185]
	v_add_u32_e32 v228, 0x80000, v156
	v_add_u32_e32 v229, 0x40000, v157
	global_store_dwordx4 v228, v[62:65], s[22:23] nt
	global_store_dwordx4 v228, v[58:61], s[22:23] offset:16 nt
	global_store_dwordx4 v228, v[54:57], s[22:23] offset:512 nt
	global_store_dwordx4 v228, v[50:53], s[22:23] offset:528 nt
	v_cvt_pk_bf16_f32 v170, v62, v63
	v_cvt_pk_bf16_f32 v171, v64, v65
	v_cvt_pk_bf16_f32 v172, v58, v59
	v_cvt_pk_bf16_f32 v173, v60, v61
	v_cvt_pk_bf16_f32 v174, v54, v55
	v_cvt_pk_bf16_f32 v175, v56, v57
	v_cvt_pk_bf16_f32 v176, v50, v51
	v_cvt_pk_bf16_f32 v177, v52, v53
	global_store_dwordx4 v229, v[170:173], s[2:3]
	global_store_dwordx4 v229, v[174:177], s[2:3] offset:256
	v_pk_mul_f32 v[222:223], v[62:63], v[62:63]
	s_nop 0
	v_pk_fma_f32 v[222:223], v[64:65], v[64:65], v[222:223]
	s_nop 0
	v_pk_fma_f32 v[222:223], v[58:59], v[58:59], v[222:223]
	s_nop 0
	v_pk_fma_f32 v[222:223], v[60:61], v[60:61], v[222:223]
	s_nop 0
	v_pk_fma_f32 v[222:223], v[54:55], v[54:55], v[222:223]
	s_nop 0
	v_pk_fma_f32 v[222:223], v[56:57], v[56:57], v[222:223]
	s_nop 0
	v_pk_fma_f32 v[222:223], v[50:51], v[50:51], v[222:223]
	s_nop 0
	v_pk_fma_f32 v[222:223], v[52:53], v[52:53], v[222:223]
	s_nop 1
	v_add_u32_e32 v227, 0xb0000, v156
	global_load_dwordx4 v[170:173], v227, s[22:23] nt
	global_load_dwordx4 v[174:177], v227, s[22:23] offset:16 nt
	global_load_dwordx4 v[178:181], v227, s[22:23] offset:512 nt
	global_load_dwordx4 v[182:185], v227, s[22:23] offset:528 nt
	s_nop 0
	v_add_f32_e32 v222, v222, v223
	ds_bpermute_b32 v224, v159, v222
	ds_bpermute_b32 v225, v160, v222
	ds_bpermute_b32 v226, v161, v222
	s_waitcnt lgkmcnt(0)
	v_add_f32_e32 v222, v222, v224
	v_add_f32_e32 v225, v225, v226
	v_add_f32_e32 v222, v222, v225
	s_mov_b64 s[16:17], exec
	s_and_b64 exec, exec, s[42:43]
	global_atomic_add_f32 v158, v222, s[8:9] offset:512
	s_mov_b64 exec, s[16:17]
	s_waitcnt vmcnt(23)
	v_pk_add_f32 v[46:47], v[46:47], v[188:189]
	v_pk_add_f32 v[48:49], v[48:49], v[190:191]
	v_pk_add_f32 v[42:43], v[42:43], v[192:193]
	v_pk_add_f32 v[44:45], v[44:45], v[194:195]
	v_pk_add_f32 v[38:39], v[38:39], v[196:197]
	v_pk_add_f32 v[40:41], v[40:41], v[198:199]
	v_pk_add_f32 v[34:35], v[34:35], v[204:205]
	v_pk_add_f32 v[36:37], v[36:37], v[206:207]
	v_add_u32_e32 v228, 0x90000, v156
	v_add_u32_e32 v229, 0x48000, v157
	global_store_dwordx4 v228, v[46:49], s[22:23] nt
	global_store_dwordx4 v228, v[42:45], s[22:23] offset:16 nt
	global_store_dwordx4 v228, v[38:41], s[22:23] offset:512 nt
	global_store_dwordx4 v228, v[34:37], s[22:23] offset:528 nt
	v_cvt_pk_bf16_f32 v188, v46, v47
	v_cvt_pk_bf16_f32 v189, v48, v49
	v_cvt_pk_bf16_f32 v190, v42, v43
	v_cvt_pk_bf16_f32 v191, v44, v45
	v_cvt_pk_bf16_f32 v192, v38, v39
	v_cvt_pk_bf16_f32 v193, v40, v41
	v_cvt_pk_bf16_f32 v194, v34, v35
	v_cvt_pk_bf16_f32 v195, v36, v37
	global_store_dwordx4 v229, v[188:191], s[2:3]
	global_store_dwordx4 v229, v[192:195], s[2:3] offset:256
	v_pk_mul_f32 v[222:223], v[46:47], v[46:47]
	s_nop 0
	v_pk_fma_f32 v[222:223], v[48:49], v[48:49], v[222:223]
	s_nop 0
	v_pk_fma_f32 v[222:223], v[42:43], v[42:43], v[222:223]
	s_nop 0
	v_pk_fma_f32 v[222:223], v[44:45], v[44:45], v[222:223]
	s_nop 0
	v_pk_fma_f32 v[222:223], v[38:39], v[38:39], v[222:223]
	s_nop 0
	v_pk_fma_f32 v[222:223], v[40:41], v[40:41], v[222:223]
	s_nop 0
	v_pk_fma_f32 v[222:223], v[34:35], v[34:35], v[222:223]
	s_nop 0
	v_pk_fma_f32 v[222:223], v[36:37], v[36:37], v[222:223]
	s_nop 0
	v_add_f32_e32 v222, v222, v223
	ds_bpermute_b32 v224, v159, v222
	ds_bpermute_b32 v225, v160, v222
	ds_bpermute_b32 v226, v161, v222
	s_waitcnt lgkmcnt(0)
; #define NTL(p) __builtin_nontemporal_load((const f32x4*)(p))
; #define NTS(v, p) __builtin_nontemporal_store((v), (f32x4*)(p))
; __device__ __forceinline__ unsigned cvt_pk_bf16(float lo, float hi) { unsigned r; asm volatile("v_cvt_pk_bf16_f32 %0, %1, %2" : "=v"(r) : "v"(lo), "v"(hi)); return r; }
;     __device__ __forceinline__ void operator()(AccT& acc, const Unit& u, int wr, int wc, int fr, int fq) const {
;     ...
;         for (int r = 0; r < 8; ++r) { const int ai = r >> 2, m = r & 3; const int row = row0 + ai * 128 + m * 16;
;             if (r < 7) { const int rn = row0 + ((r + 1) >> 2) * 128 + ((r + 1) & 3) * 16; const float* xr = (rn < HALF_TOK ? x0 + (size_t)rn * DM : x1 + (size_t)(rn - HALF_TOK) * DM) + col0;
;                 xv[(r + 1) & 1][0] = NTL(xr); xv[(r + 1) & 1][1] = NTL(xr + 4); xv[(r + 1) & 1][2] = NTL(xr + 128); xv[(r + 1) & 1][3] = NTL(xr + 132); }
;             float* hr = H + (size_t)row * DM + col0; float ss = 0.f;
; #pragma unroll
;             for (int bj = 0; bj < 2; ++bj) {
;                 f32x4 v0 = acc[ai][bj][m][0] + xv[r & 1][2 * bj], v1 = acc[ai][bj][m][1] + xv[r & 1][2 * bj + 1];
;                 NTS(v0, hr + bj * 128); NTS(v1, hr + bj * 128 + 4);
;                 u32x4 w; w.x = cvt_pk_bf16(v0[0], v0[1]); w.y = cvt_pk_bf16(v0[2], v0[3]); w.z = cvt_pk_bf16(v1[0], v1[1]); w.w = cvt_pk_bf16(v1[2], v1[3]);
;                 *(u32x4*)(HB + (size_t)row * DM + col0 + bj * 128) = w;
; #pragma unroll
;                 for (int j = 0; j < 4; ++j) ss += v0[j] * v0[j] + v1[j] * v1[j]; }
;             ss += __shfl_xor(ss, 16); ss += __shfl_xor(ss, 32);
;             if (fq == 0) unsafeAtomicAdd(rss + row, ss); __builtin_amdgcn_sched_barrier(0); }
	v_add_f32_e32 v222, v222, v224
	v_add_f32_e32 v225, v225, v226
	v_add_f32_e32 v222, v222, v225
	s_mov_b64 s[16:17], exec
	s_and_b64 exec, exec, s[42:43]
	global_atomic_add_f32 v158, v222, s[8:9] offset:576
	s_mov_b64 exec, s[16:17]
	s_waitcnt vmcnt(19)
	v_pk_add_f32 v[30:31], v[30:31], v[130:131]
	v_pk_add_f32 v[32:33], v[32:33], v[132:133]
	v_pk_add_f32 v[26:27], v[26:27], v[134:135]
	v_pk_add_f32 v[28:29], v[28:29], v[136:137]
	v_pk_add_f32 v[22:23], v[22:23], v[138:139]
	v_pk_add_f32 v[24:25], v[24:25], v[140:141]
	v_pk_add_f32 v[18:19], v[18:19], v[142:143]
	v_pk_add_f32 v[20:21], v[20:21], v[144:145]
	v_add_u32_e32 v228, 0xa0000, v156
	v_add_u32_e32 v229, 0x50000, v157
	global_store_dwordx4 v228, v[30:33], s[22:23] nt
	global_store_dwordx4 v228, v[26:29], s[22:23] offset:16 nt
	global_store_dwordx4 v228, v[22:25], s[22:23] offset:512 nt
	global_store_dwordx4 v228, v[18:21], s[22:23] offset:528 nt
	v_cvt_pk_bf16_f32 v130, v30, v31
	v_cvt_pk_bf16_f32 v131, v32, v33
	v_cvt_pk_bf16_f32 v132, v26, v27
	v_cvt_pk_bf16_f32 v133, v28, v29
	v_cvt_pk_bf16_f32 v134, v22, v23
	v_cvt_pk_bf16_f32 v135, v24, v25
	v_cvt_pk_bf16_f32 v136, v18, v19
	v_cvt_pk_bf16_f32 v137, v20, v21
	global_store_dwordx4 v229, v[130:133], s[2:3]
	global_store_dwordx4 v229, v[134:137], s[2:3] offset:256
	v_pk_mul_f32 v[222:223], v[30:31], v[30:31]
	s_nop 0
	v_pk_fma_f32 v[222:223], v[32:33], v[32:33], v[222:223]
	s_nop 0
	v_pk_fma_f32 v[222:223], v[26:27], v[26:27], v[222:223]
	s_nop 0
	v_pk_fma_f32 v[222:223], v[28:29], v[28:29], v[222:223]
	s_nop 0
	v_pk_fma_f32 v[222:223], v[22:23], v[22:23], v[222:223]
	s_nop 0
	v_pk_fma_f32 v[222:223], v[24:25], v[24:25], v[222:223]
	s_nop 0
	v_pk_fma_f32 v[222:223], v[18:19], v[18:19], v[222:223]
	s_nop 0
	v_pk_fma_f32 v[222:223], v[20:21], v[20:21], v[222:223]
	s_nop 0
	v_add_f32_e32 v222, v222, v223
	ds_bpermute_b32 v224, v159, v222
	ds_bpermute_b32 v225, v160, v222
	ds_bpermute_b32 v226, v161, v222
	s_waitcnt lgkmcnt(0)
	v_add_f32_e32 v222, v222, v224
	v_add_f32_e32 v225, v225, v226
	v_add_f32_e32 v222, v222, v225
	s_mov_b64 s[16:17], exec
	s_and_b64 exec, exec, s[42:43]
	global_atomic_add_f32 v158, v222, s[8:9] offset:640
	s_mov_b64 exec, s[16:17]
	s_waitcnt vmcnt(15)
	v_pk_add_f32 v[14:15], v[14:15], v[170:171]
	v_pk_add_f32 v[16:17], v[16:17], v[172:173]
	v_pk_add_f32 v[10:11], v[10:11], v[174:175]
	v_pk_add_f32 v[12:13], v[12:13], v[176:177]
	v_pk_add_f32 v[6:7], v[6:7], v[178:179]
	v_pk_add_f32 v[8:9], v[8:9], v[180:181]
	v_pk_add_f32 v[2:3], v[2:3], v[182:183]
	v_pk_add_f32 v[4:5], v[4:5], v[184:185]
	v_add_u32_e32 v228, 0xb0000, v156
	v_add_u32_e32 v229, 0x58000, v157
	global_store_dwordx4 v228, v[14:17], s[22:23] nt
	global_store_dwordx4 v228, v[10:13], s[22:23] offset:16 nt
	global_store_dwordx4 v228, v[6:9], s[22:23] offset:512 nt
	global_store_dwordx4 v228, v[2:5], s[22:23] offset:528 nt
	v_cvt_pk_bf16_f32 v170, v14, v15
	v_cvt_pk_bf16_f32 v171, v16, v17
	v_cvt_pk_bf16_f32 v172, v10, v11
	v_cvt_pk_bf16_f32 v173, v12, v13
	v_cvt_pk_bf16_f32 v174, v6, v7
	v_cvt_pk_bf16_f32 v175, v8, v9
	v_cvt_pk_bf16_f32 v176, v2, v3
	v_cvt_pk_bf16_f32 v177, v4, v5
	global_store_dwordx4 v229, v[170:173], s[2:3]
	global_store_dwordx4 v229, v[174:177], s[2:3] offset:256
	v_pk_mul_f32 v[222:223], v[14:15], v[14:15]
	s_nop 0
	v_pk_fma_f32 v[222:223], v[16:17], v[16:17], v[222:223]
	s_nop 0
	v_pk_fma_f32 v[222:223], v[10:11], v[10:11], v[222:223]
	s_nop 0
	v_pk_fma_f32 v[222:223], v[12:13], v[12:13], v[222:223]
	s_nop 0
	v_pk_fma_f32 v[222:223], v[6:7], v[6:7], v[222:223]
	s_nop 0
	v_pk_fma_f32 v[222:223], v[8:9], v[8:9], v[222:223]
	s_nop 0
	v_pk_fma_f32 v[222:223], v[2:3], v[2:3], v[222:223]
	s_nop 0
	v_pk_fma_f32 v[222:223], v[4:5], v[4:5], v[222:223]
	s_nop 0
	v_add_f32_e32 v222, v222, v223
	ds_bpermute_b32 v224, v159, v222
	ds_bpermute_b32 v225, v160, v222
	ds_bpermute_b32 v226, v161, v222
	s_waitcnt lgkmcnt(0)
	v_add_f32_e32 v222, v222, v224
	v_add_f32_e32 v225, v225, v226
	v_add_f32_e32 v222, v222, v225
	s_mov_b64 s[16:17], exec
	s_and_b64 exec, exec, s[42:43]
	global_atomic_add_f32 v158, v222, s[8:9] offset:704
	s_mov_b64 exec, s[16:17]
	s_mov_b64 s[16:17], 0
	s_branch .LBB0_836
